# stack7 without the ff1 write-through stores: phase-1 row prefetch pipeline + in-proj/ff1 epilogue sum-of-squares load hoist
# baseline (speedup 1.0000x reference)
; #define WAIT_V0() asm volatile("s_waitcnt vmcnt(0)" ::: "memory")
; #define G_STAGE_A(Ap, buf, kt) do { const char* ab_ = (const char*)(Ap) + (size_t)(kt) * 128; \
;       _Pragma("unroll") for (int i = 0; i < 4; ++i) \
;         __builtin_amdgcn_global_load_lds((const unsigned*)(ab_ + soff[i]), (LDSP unsigned*)(G_SA(buf) + wid * 1024 + i * 8192), 16, 0, 0); } while (0)
; #define G_STAGE_B(Bp, buf, kt) do { const char* bb_ = (const char*)(Bp) + (size_t)(kt) * 128; \
;       _Pragma("unroll") for (int i = 0; i < 4; ++i) \
;         __builtin_amdgcn_global_load_lds((const unsigned*)(bb_ + soff[i]), (LDSP unsigned*)(G_SB(buf) + wid * 1024 + i * 8192), 16, 0, 0); } while (0)
; #define G_RDA(AF, buf, ks, mh) do { _Pragma("unroll") for (int m = 0; m < 4; ++m) AF[m] = *(const LDSP bf16x8*)(G_SA(buf) + aoff + ((mh) * 4 + m) * 2048 + (ks) * 1024); } while (0)
; #define G_RDB(BF, buf, ks) do { _Pragma("unroll") for (int n = 0; n < 4; ++n) BF[n] = *(const LDSP bf16x8*)(G_SB(buf) + boff + n * 2048 + (ks) * 1024); } while (0)
; #define G_SB0() __builtin_amdgcn_sched_barrier(0)
; template <int EK>
; DI void gemm_stream(const Params& p, int l, const bf16_t* __restrict__ A, const bf16_t* __restrict__ Bt, int M, int N, int K, ldsp_t shm) {
;     ...
;         for (int t = 0; t < nt; ++t) {
;             const int cur = t & 1;
;             G_RDA(Aa, cur, 0, 0); G_RDB(Bk0, cur, 0);
;             if (t + 1 < nt) G_STAGE_B(Bb, cur ^ 1, t + 1);
;             else if (has_next) G_STAGE_B(Bb2, cur ^ 1, 0);
;             G_SB0();
;             if (t > 0) G_MMA(Ab_, Bk1, 1);
;             G_SB0();
;             if (t + 1 < nt) G_STAGE_A(Ab, cur ^ 1, t + 1);
;             else if (has_next) G_STAGE_A(Ab2, cur ^ 1, 0);
;             G_RDA(Ab_, cur, 0, 1);
;             G_MMA(Aa, Bk0, 0); G_SB0();
;             G_RDA(Aa, cur, 1, 0); G_RDB(Bk1, cur, 1);
;             G_MMA(Ab_, Bk0, 1); G_SB0();
;             G_RDA(Ab_, cur, 1, 1);
;             G_MMA(Aa, Bk1, 0); G_SB0();
;             asm volatile("s_waitcnt lgkmcnt(0)" ::: "memory");
;             WAIT_V0(); __syncthreads();
;         }
;         G_MMA(Ab_, Bk1, 1);
.LBB0_103:
	v_add_u32_e32 v80, 0x12000, v218
	v_add_u32_e32 v132, 0x12800, v218
	v_add_u32_e32 v136, 0x13000, v218
	v_add_u32_e32 v140, 0x13800, v218
	ds_read_b128 v[80:83], v80
	ds_read_b128 v[132:135], v132
	ds_read_b128 v[136:139], v136
	ds_read_b128 v[140:143], v140
	s_setprio 1
	s_waitcnt lgkmcnt(0)
	v_mfma_f32_16x16x32_bf16 v[60:63], v[160:163], v[188:191], v[60:63]
	v_mfma_f32_16x16x32_bf16 v[56:59], v[164:167], v[188:191], v[56:59]
	v_mfma_f32_16x16x32_bf16 v[52:55], v[168:171], v[188:191], v[52:55]
	v_mfma_f32_16x16x32_bf16 v[48:51], v[172:175], v[188:191], v[48:51]
	v_mfma_f32_16x16x32_bf16 v[44:47], v[160:163], v[180:183], v[44:47]
	v_mfma_f32_16x16x32_bf16 v[40:43], v[164:167], v[180:183], v[40:43]
	v_mfma_f32_16x16x32_bf16 v[36:39], v[168:171], v[180:183], v[36:39]
	v_mfma_f32_16x16x32_bf16 v[32:35], v[172:175], v[180:183], v[32:35]
	v_mfma_f32_16x16x32_bf16 v[28:31], v[160:163], v[184:187], v[28:31]
	v_mfma_f32_16x16x32_bf16 v[24:27], v[164:167], v[184:187], v[24:27]
	v_mfma_f32_16x16x32_bf16 v[20:23], v[168:171], v[184:187], v[20:23]
	v_mfma_f32_16x16x32_bf16 v[16:19], v[172:175], v[184:187], v[16:19]
	v_mfma_f32_16x16x32_bf16 v[12:15], v[160:163], v[176:179], v[12:15]
	v_mfma_f32_16x16x32_bf16 v[8:11], v[164:167], v[176:179], v[8:11]
	v_mfma_f32_16x16x32_bf16 v[4:7], v[168:171], v[176:179], v[4:7]
	v_mfma_f32_16x16x32_bf16 v[0:3], v[172:175], v[176:179], v[0:3]
	s_setprio 0
	v_add_u32_e32 v144, 0x10400, v218
	v_add_u32_e32 v148, 0x10c00, v218
	v_add_u32_e32 v152, 0x11400, v218
	v_add_u32_e32 v156, 0x11c00, v218
	v_add_u32_e32 v176, 0x18400, v219
	v_add_u32_e32 v180, 0x18c00, v219
	v_add_u32_e32 v184, 0x19400, v219
	v_add_u32_e32 v188, 0x19c00, v219
	ds_read_b128 v[144:147], v144
	ds_read_b128 v[148:151], v148
	ds_read_b128 v[152:155], v152
	ds_read_b128 v[156:159], v156
	ds_read_b128 v[176:179], v176
	ds_read_b128 v[180:183], v180
	ds_read_b128 v[184:187], v184
	ds_read_b128 v[188:191], v188
	s_setprio 1
	v_mfma_f32_16x16x32_bf16 v[128:131], v[160:163], v[80:83], v[128:131]
	v_mfma_f32_16x16x32_bf16 v[124:127], v[164:167], v[80:83], v[124:127]
	v_mfma_f32_16x16x32_bf16 v[120:123], v[168:171], v[80:83], v[120:123]
	v_mfma_f32_16x16x32_bf16 v[116:119], v[172:175], v[80:83], v[116:119]
	v_mfma_f32_16x16x32_bf16 v[112:115], v[160:163], v[132:135], v[112:115]
	v_mfma_f32_16x16x32_bf16 v[194:197], v[164:167], v[132:135], v[108:111]
	v_mfma_f32_16x16x32_bf16 v[198:201], v[168:171], v[132:135], v[104:107]
	v_mfma_f32_16x16x32_bf16 v[132:135], v[172:175], v[132:135], v[100:103]
	v_mfma_f32_16x16x32_bf16 v[204:207], v[160:163], v[136:139], v[96:99]
	v_mfma_f32_16x16x32_bf16 v[210:213], v[164:167], v[136:139], v[92:95]
	v_mfma_f32_16x16x32_bf16 v[214:217], v[168:171], v[136:139], v[88:91]
	v_mfma_f32_16x16x32_bf16 v[136:139], v[172:175], v[136:139], v[84:87]
	v_mfma_f32_16x16x32_bf16 v[160:163], v[160:163], v[140:143], v[64:67]
	v_mfma_f32_16x16x32_bf16 v[164:167], v[164:167], v[140:143], v[68:71]
	v_mfma_f32_16x16x32_bf16 v[168:171], v[168:171], v[140:143], v[76:79]
	v_mfma_f32_16x16x32_bf16 v[140:143], v[172:175], v[140:143], v[72:75]
	s_setprio 0
	v_add_u32_e32 v64, 0x12400, v218
	v_add_u32_e32 v68, 0x12c00, v218
	ds_read_b128 v[64:67], v64
	ds_read_b128 v[172:175], v68
	v_add_u32_e32 v68, 0x13400, v218
	v_add_u32_e32 v69, 0x13c00, v218
	ds_read_b128 v[218:221], v68
	ds_read_b128 v[222:225], v69
	s_setprio 1
	s_waitcnt lgkmcnt(0)
	v_mfma_f32_16x16x32_bf16 v[226:229], v[176:179], v[144:147], v[60:63]
	v_mfma_f32_16x16x32_bf16 v[230:233], v[180:183], v[144:147], v[56:59]
	v_mfma_f32_16x16x32_bf16 v[234:237], v[184:187], v[144:147], v[52:55]
	v_mfma_f32_16x16x32_bf16 v[238:241], v[188:191], v[144:147], v[48:51]
	v_mfma_f32_16x16x32_bf16 v[242:245], v[176:179], v[148:151], v[44:47]
	v_mfma_f32_16x16x32_bf16 v[246:249], v[180:183], v[148:151], v[40:43]
	v_mfma_f32_16x16x32_bf16 v[144:147], v[184:187], v[148:151], v[36:39]
	v_mfma_f32_16x16x32_bf16 v[48:51], v[188:191], v[148:151], v[32:35]
	v_mfma_f32_16x16x32_bf16 v[108:111], v[176:179], v[152:155], v[28:31]
	v_mfma_f32_16x16x32_bf16 v[104:107], v[180:183], v[152:155], v[24:27]
	v_mfma_f32_16x16x32_bf16 v[100:103], v[184:187], v[152:155], v[20:23]
	v_mfma_f32_16x16x32_bf16 v[96:99], v[188:191], v[152:155], v[16:19]
	v_mfma_f32_16x16x32_bf16 v[92:95], v[176:179], v[156:159], v[12:15]
	v_mfma_f32_16x16x32_bf16 v[88:91], v[180:183], v[156:159], v[8:11]
	v_mfma_f32_16x16x32_bf16 v[84:87], v[184:187], v[156:159], v[4:7]
	v_mfma_f32_16x16x32_bf16 v[80:83], v[188:191], v[156:159], v[0:3]
	s_setprio 0
	s_waitcnt lgkmcnt(0)
	s_waitcnt vmcnt(0)
	s_waitcnt vmcnt(0)
	s_barrier
; #define G_STAGE_B(Bp, buf, kt) do { const char* bb_ = (const char*)(Bp) + (size_t)(kt) * 128; \
;       _Pragma("unroll") for (int i = 0; i < 4; ++i) \
;         __builtin_amdgcn_global_load_lds((const unsigned*)(bb_ + soff[i]), (LDSP unsigned*)(G_SB(buf) + wid * 1024 + i * 8192), 16, 0, 0); } while (0)
; #define G_MMA(AF, BF, mh) do { __builtin_amdgcn_s_setprio(1); \
;             _Pragma("unroll") for (int m = 0; m < 4; ++m) _Pragma("unroll") for (int n = 0; n < 4; ++n) \
;                 acc[(mh) * 4 + m][n] = __builtin_amdgcn_mfma_f32_16x16x32_bf16(BF[n], AF[m], acc[(mh) * 4 + m][n], 0, 0, 0); \
;             __builtin_amdgcn_s_setprio(0); } while (0)
; template <int EK>
; DI void gemm_stream(const Params& p, int l, const bf16_t* __restrict__ A, const bf16_t* __restrict__ Bt, int M, int N, int K, ldsp_t shm) {
;     ...
;         G_MMA(Ab_, Bk1, 1);
;         G_SB0();
;         {
;             int tid2 = threadIdx.x, pme = pm, pne = pn;
;             asm volatile("" : "+v"(tid2), "+s"(pme), "+s"(pne));
;             TileCtx tc;
;             tc.wid = tid2 >> 6; tc.lane = tid2 & 63; tc.wr = tc.wid >> 2; tc.wc = tc.wid & 3; tc.fr = tc.lane & 15; tc.fq = tc.lane >> 4; tc.l = l;
;             tc.brow = pme * 256; tc.bcol = pne * 256; tc.pn = pne;
;             ldsp_t ex = shm + G_STAGE_B + tc.wid * 8192;
;             if (EK == 0 || EK == 2) {
;                 const int cond = tc.brow < NLAT ? (tc.brow >> 12) : 4;
;                 const float* ssp = p.ss + ((size_t)(l * 2 + (EK == 0 ? 0 : 1)) * NTOK + tc.brow + tc.wr * 128 + tc.fr) * 16 + tc.fq * 4;
;                 const float* shw = (EK == 0 ? p.shw_in + ((size_t)l * 5 + cond) * IN_DIM : p.shw_ff1 + ((size_t)l * 5 + cond) * FF) + tc.bcol + tc.wc * 64 + tc.fq * 4;
;                 f32x4 shv[4];
; #pragma unroll
;                 for (int n = 0; n < 4; ++n) shv[n] = *(const f32x4*)(shw + n * 16);
; #pragma unroll
;                 for (int m = 0; m < 8; ++m) {
;                     const f32x4 pp = *(const f32x4*)(ssp + m * 256);
;                     float sq = pp[0] + pp[1] + pp[2] + pp[3];
;                     sq += __shfl_xor(sq, 16);
;                     sq += __shfl_xor(sq, 32);
;                     const float rstd = rsqrtf(sq * (1.f / DM) + EPS);
; #pragma unroll
;                     for (int n = 0; n < 4; ++n) acc[m][n] = acc[m][n] * rstd + shv[n];
	s_setprio 1
	v_mfma_f32_16x16x32_bf16 v[76:79], v[176:179], v[64:67], v[128:131]
	v_mfma_f32_16x16x32_bf16 v[72:75], v[180:183], v[64:67], v[124:127]
	v_mfma_f32_16x16x32_bf16 v[68:71], v[184:187], v[64:67], v[120:123]
	v_mfma_f32_16x16x32_bf16 v[64:67], v[188:191], v[64:67], v[116:119]
	v_mfma_f32_16x16x32_bf16 v[60:63], v[176:179], v[172:175], v[112:115]
	v_mfma_f32_16x16x32_bf16 v[56:59], v[180:183], v[172:175], v[194:197]
	v_mfma_f32_16x16x32_bf16 v[52:55], v[184:187], v[172:175], v[198:201]
	v_mfma_f32_16x16x32_bf16 v[172:175], v[188:191], v[172:175], v[132:135]
	v_mfma_f32_16x16x32_bf16 v[28:31], v[176:179], v[218:221], v[204:207]
	v_mfma_f32_16x16x32_bf16 v[24:27], v[180:183], v[218:221], v[210:213]
	v_mfma_f32_16x16x32_bf16 v[20:23], v[184:187], v[218:221], v[214:217]
	v_mfma_f32_16x16x32_bf16 v[16:19], v[188:191], v[218:221], v[136:139]
	v_mfma_f32_16x16x32_bf16 v[12:15], v[176:179], v[222:225], v[160:163]
	v_mfma_f32_16x16x32_bf16 v[8:11], v[180:183], v[222:225], v[164:167]
	v_mfma_f32_16x16x32_bf16 v[4:7], v[184:187], v[222:225], v[168:171]
	v_mfma_f32_16x16x32_bf16 v[0:3], v[188:191], v[222:225], v[140:143]
	s_setprio 0
	v_mov_b32_e32 v158, v252
	s_lshl_b32 s35, s51, 8
	s_min_i32 s4, s35, 0x4000
	s_lshl_b32 s42, s50, 8
	s_ashr_i32 s4, s4, 12
	s_ashr_i32 s5, s35, 31
	v_lshlrev_b32_e32 v32, 7, v158
	s_add_u32 s37, s11, s35
	v_and_b32_e32 v159, 15, v158
	v_and_b32_e32 v160, 0xffffe000, v32
	s_addc_u32 s5, s10, s5
	v_ashrrev_i32_e32 v32, 1, v158
	v_and_b32_e32 v112, 0xffffff80, v32
	v_or_b32_e32 v32, s37, v159
	v_mov_b32_e32 v33, s5
	s_ashr_i32 s5, s4, 31
	s_mul_i32 s37, s48, 5
	s_add_u32 s4, s37, s4
	s_mul_hi_i32 s37, s48, 5
	s_addc_u32 s5, s37, s5
	s_lshl_b64 s[4:5], s[4:5], 14
	s_add_u32 s37, s78, s4
	s_addc_u32 s50, s79, s5
	s_ashr_i32 s43, s42, 31
	v_ashrrev_i32_e32 v113, 31, v112
	s_lshl_b64 s[4:5], s[42:43], 2
	v_lshl_add_u64 v[32:33], v[32:33], 0, v[112:113]
	s_add_u32 s4, s37, s4
	v_and_b32_e32 v113, 0xc0, v158
	v_lshlrev_b64 v[114:115], 6, v[32:33]
	s_addc_u32 s5, s50, s5
	v_lshlrev_b32_e32 v192, 2, v113
	v_lshl_add_u64 v[32:33], s[4:5], 0, v[192:193]
	v_and_b32_e32 v192, 48, v158
	v_lshl_add_u64 v[114:115], s[74:75], 0, v[114:115]
	v_lshl_add_u64 v[150:151], v[114:115], 0, v[192:193]
	v_xor_b32_e32 v114, 16, v202
	v_cmp_lt_i32_e32 vcc, v114, v203
	v_lshl_add_u64 v[32:33], v[32:33], 0, v[192:193]
	global_load_dwordx4 v[44:47], v[32:33], off
	global_load_dwordx4 v[40:43], v[32:33], off offset:64
	global_load_dwordx4 v[36:39], v[32:33], off offset:128
	s_nop 0
	global_load_dwordx4 v[32:35], v[32:33], off offset:192
	v_cndmask_b32_e32 v114, v202, v114, vcc
	v_cmp_lt_i32_e32 vcc, v209, v203
	v_lshlrev_b32_e32 v162, 2, v114
	s_mov_b32 s4, 0x358637bd
	v_cndmask_b32_e32 v114, v202, v209, vcc
	v_lshlrev_b32_e32 v161, 2, v114
	global_load_dwordx4 v[114:117], v[150:151], off
	global_load_dwordx4 v[118:121], v[150:151], off offset:1024
	global_load_dwordx4 v[176:179], v[150:151], off offset:2048
	global_load_dwordx4 v[180:183], v[150:151], off offset:3072
	v_mov_b32_e32 v194, s29
	v_mov_b32_e32 v195, 0
	v_lshl_add_u64 v[194:195], v[150:151], 0, v[194:195]
	global_load_dwordx4 v[184:187], v[194:195], off
	global_load_dwordx4 v[188:191], v[194:195], off offset:1024
	global_load_dwordx4 v[218:221], v[194:195], off offset:2048
	global_load_dwordx4 v[222:225], v[194:195], off offset:3072
	v_mov_b64_e32 v[166:167], s[4:5]
	s_mov_b32 s16, 0x3a800000
	v_lshlrev_b32_e32 v192, 1, v113
	s_mov_b32 s50, s36
	s_mov_b32 s51, s34
	s_waitcnt vmcnt(7)
	v_mov_b32_e32 v123, v114
	s_waitcnt vmcnt(6)
	v_mov_b32_e32 v122, v118
	v_mov_b32_e32 v114, v119
	v_pk_add_f32 v[114:115], v[122:123], v[114:115]
	v_mov_b32_e32 v118, v120
	v_mov_b32_e32 v119, v116
	v_pk_add_f32 v[114:115], v[118:119], v[114:115]
	v_mov_b32_e32 v116, v121
	v_pk_add_f32 v[114:115], v[116:117], v[114:115]
	ds_bpermute_b32 v117, v162, v115
	ds_bpermute_b32 v116, v162, v114
	s_waitcnt lgkmcnt(0)
	v_pk_add_f32 v[114:115], v[114:115], v[116:117]
	ds_bpermute_b32 v117, v161, v115
	ds_bpermute_b32 v116, v161, v114
	s_waitcnt lgkmcnt(0)
	v_pk_add_f32 v[114:115], v[114:115], v[116:117]
	s_nop 0
	v_pk_fma_f32 v[114:115], v[114:115], s[16:17], v[166:167] op_sel_hi:[1,0,0]
	s_nop 0
	v_mul_f32_e32 v116, 0x4b800000, v115
	v_cmp_gt_f32_e64 s[4:5], s92, v115
	v_cmp_gt_f32_e32 vcc, s92, v114
	s_nop 0
	v_cndmask_b32_e64 v115, v115, v116, s[4:5]
	v_rsq_f32_e32 v115, v115
	s_nop 0
	v_mul_f32_e32 v116, 0x45800000, v115
	v_cndmask_b32_e64 v116, v115, v116, s[4:5]
	v_mul_f32_e32 v115, 0x4b800000, v114
	v_cndmask_b32_e32 v114, v114, v115, vcc
	v_rsq_f32_e32 v114, v114
	v_pk_fma_f32 v[142:143], v[228:229], v[116:117], v[46:47] op_sel_hi:[1,0,1]
	v_pk_fma_f32 v[164:165], v[226:227], v[116:117], v[44:45] op_sel_hi:[1,0,1]
	v_pk_fma_f32 v[138:139], v[232:233], v[116:117], v[42:43] op_sel_hi:[1,0,1]
	v_mul_f32_e32 v115, 0x45800000, v114
	v_pk_fma_f32 v[140:141], v[230:231], v[116:117], v[40:41] op_sel_hi:[1,0,1]
	v_pk_fma_f32 v[134:135], v[236:237], v[116:117], v[38:39] op_sel_hi:[1,0,1]
	v_pk_fma_f32 v[136:137], v[234:235], v[116:117], v[36:37] op_sel_hi:[1,0,1]
	v_pk_fma_f32 v[130:131], v[240:241], v[116:117], v[34:35] op_sel_hi:[1,0,1]
	v_pk_fma_f32 v[132:133], v[238:239], v[116:117], v[32:33] op_sel_hi:[1,0,1]
	v_cndmask_b32_e32 v116, v114, v115, vcc
	v_pk_fma_f32 v[126:127], v[244:245], v[116:117], v[46:47] op_sel_hi:[1,0,1]
	v_pk_fma_f32 v[128:129], v[242:243], v[116:117], v[44:45] op_sel_hi:[1,0,1]
	v_pk_fma_f32 v[122:123], v[248:249], v[116:117], v[42:43] op_sel_hi:[1,0,1]
	v_pk_fma_f32 v[124:125], v[246:247], v[116:117], v[40:41] op_sel_hi:[1,0,1]
	v_pk_fma_f32 v[118:119], v[146:147], v[116:117], v[38:39] op_sel_hi:[1,0,1]
	v_pk_fma_f32 v[120:121], v[144:145], v[116:117], v[36:37] op_sel_hi:[1,0,1]
	v_pk_fma_f32 v[114:115], v[50:51], v[116:117], v[34:35] op_sel_hi:[1,0,1]
	v_pk_fma_f32 v[116:117], v[48:49], v[116:117], v[32:33] op_sel_hi:[1,0,1]
	s_waitcnt vmcnt(4)
; DI unsigned pk2(float a, float b) { f32x2 v = {a, b}; bf2_t r = __builtin_convertvector(v, bf2_t); return __builtin_bit_cast(unsigned, r); }
;     static DI void run(const f32x4 (&acc)[8][4], const TileCtx& tc, const Params& p, ldsp_t wb) {
;     ...
;             for (int mm = 0; mm < 4; ++mm) {
;                 const int m = h * 4 + mm;
; #pragma unroll
;                 for (int n = 0; n < 4; ++n) {
;                     f32x4 a = acc[m][n];
; #pragma unroll
;                     for (int j = 0; j < 4; ++j) { const float r = fmaxf(a[j], 0.f); a[j] = r * r; }
;                     u32x2 w; w[0] = pk2(a[0], a[1]); w[1] = pk2(a[2], a[3]);
; template <int EK>
; DI void gemm_stream(const Params& p, int l, const bf16_t* __restrict__ A, const bf16_t* __restrict__ Bt, int M, int N, int K, ldsp_t shm) {
;     ...
; #pragma unroll
;                 for (int m = 0; m < 8; ++m) {
;                     const f32x4 pp = *(const f32x4*)(ssp + m * 256);
;                     float sq = pp[0] + pp[1] + pp[2] + pp[3];
;                     sq += __shfl_xor(sq, 16);
;                     sq += __shfl_xor(sq, 32);
;                     const float rstd = rsqrtf(sq * (1.f / DM) + EPS);
; #pragma unroll
;                     for (int n = 0; n < 4; ++n) acc[m][n] = acc[m][n] * rstd + shv[n];
;                 }
	v_mov_b64_e32 v[48:49], v[176:177]
	v_mov_b64_e32 v[50:51], v[178:179]
	v_mov_b64_e32 v[144:145], v[180:181]
	v_mov_b64_e32 v[146:147], v[182:183]
	v_mov_b32_e32 v149, v48
	v_mov_b32_e32 v148, v144
	v_mov_b32_e32 v48, v145
	v_pk_add_f32 v[48:49], v[148:149], v[48:49]
	v_mov_b32_e32 v144, v146
	v_mov_b32_e32 v145, v50
	v_pk_add_f32 v[48:49], v[144:145], v[48:49]
	v_mov_b32_e32 v50, v147
	v_pk_add_f32 v[48:49], v[50:51], v[48:49]
	ds_bpermute_b32 v51, v162, v49
	ds_bpermute_b32 v50, v162, v48
	s_waitcnt lgkmcnt(0)
	v_pk_add_f32 v[48:49], v[48:49], v[50:51]
	ds_bpermute_b32 v51, v161, v49
	ds_bpermute_b32 v50, v161, v48
	s_waitcnt lgkmcnt(0)
	v_pk_add_f32 v[48:49], v[48:49], v[50:51]
	s_nop 0
	v_pk_fma_f32 v[48:49], v[48:49], s[16:17], v[166:167] op_sel_hi:[1,0,0]
	s_nop 0
	v_mul_f32_e32 v50, 0x4b800000, v49
	v_cmp_gt_f32_e64 s[4:5], s92, v49
	v_cmp_gt_f32_e32 vcc, s92, v48
	s_nop 0
	v_cndmask_b32_e64 v49, v49, v50, s[4:5]
	v_rsq_f32_e32 v49, v49
	s_nop 0
	v_mul_f32_e32 v50, 0x45800000, v49
	v_cndmask_b32_e64 v50, v49, v50, s[4:5]
	v_mul_f32_e32 v49, 0x4b800000, v48
	v_cndmask_b32_e32 v48, v48, v49, vcc
	v_rsq_f32_e32 v48, v48
	v_pk_fma_f32 v[110:111], v[110:111], v[50:51], v[46:47] op_sel_hi:[1,0,1]
	v_pk_fma_f32 v[148:149], v[108:109], v[50:51], v[44:45] op_sel_hi:[1,0,1]
	v_pk_fma_f32 v[106:107], v[106:107], v[50:51], v[42:43] op_sel_hi:[1,0,1]
	v_mul_f32_e32 v49, 0x45800000, v48
	v_cndmask_b32_e32 v48, v48, v49, vcc
	v_add_co_u32_e32 v156, vcc, s29, v150
	v_pk_fma_f32 v[104:105], v[104:105], v[50:51], v[40:41] op_sel_hi:[1,0,1]
	s_nop 0
	v_addc_co_u32_e32 v157, vcc, 0, v151, vcc
	v_pk_fma_f32 v[102:103], v[102:103], v[50:51], v[38:39] op_sel_hi:[1,0,1]
	v_pk_fma_f32 v[100:101], v[100:101], v[50:51], v[36:37] op_sel_hi:[1,0,1]
	v_pk_fma_f32 v[98:99], v[98:99], v[50:51], v[34:35] op_sel_hi:[1,0,1]
	v_pk_fma_f32 v[96:97], v[96:97], v[50:51], v[32:33] op_sel_hi:[1,0,1]
	v_pk_fma_f32 v[94:95], v[94:95], v[48:49], v[46:47] op_sel_hi:[1,0,1]
	v_pk_fma_f32 v[92:93], v[92:93], v[48:49], v[44:45] op_sel_hi:[1,0,1]
	v_pk_fma_f32 v[90:91], v[90:91], v[48:49], v[42:43] op_sel_hi:[1,0,1]
	v_pk_fma_f32 v[88:89], v[88:89], v[48:49], v[40:41] op_sel_hi:[1,0,1]
	v_pk_fma_f32 v[86:87], v[86:87], v[48:49], v[38:39] op_sel_hi:[1,0,1]
	v_pk_fma_f32 v[84:85], v[84:85], v[48:49], v[36:37] op_sel_hi:[1,0,1]
	v_pk_fma_f32 v[82:83], v[82:83], v[48:49], v[34:35] op_sel_hi:[1,0,1]
	v_pk_fma_f32 v[80:81], v[80:81], v[48:49], v[32:33] op_sel_hi:[1,0,1]
	s_waitcnt vmcnt(2)
	v_mov_b64_e32 v[48:49], v[184:185]
	v_mov_b64_e32 v[50:51], v[186:187]
	v_mov_b64_e32 v[144:145], v[188:189]
	v_mov_b64_e32 v[146:147], v[190:191]
	v_mov_b32_e32 v109, v48
	v_mov_b32_e32 v108, v144
	v_mov_b32_e32 v48, v145
	v_pk_add_f32 v[48:49], v[108:109], v[48:49]
	v_mov_b32_e32 v108, v146
	v_mov_b32_e32 v109, v50
	v_pk_add_f32 v[48:49], v[108:109], v[48:49]
	v_mov_b32_e32 v50, v147
	v_pk_add_f32 v[48:49], v[50:51], v[48:49]
	ds_bpermute_b32 v51, v162, v49
	ds_bpermute_b32 v50, v162, v48
	s_waitcnt lgkmcnt(0)
	v_pk_add_f32 v[48:49], v[48:49], v[50:51]
	ds_bpermute_b32 v51, v161, v49
	ds_bpermute_b32 v50, v161, v48
	s_waitcnt lgkmcnt(0)
	v_pk_add_f32 v[48:49], v[48:49], v[50:51]
	s_nop 0
	v_pk_fma_f32 v[48:49], v[48:49], s[16:17], v[166:167] op_sel_hi:[1,0,0]
	s_nop 0
	v_mul_f32_e32 v50, 0x4b800000, v49
	v_cmp_gt_f32_e64 s[4:5], s92, v49
	v_cmp_gt_f32_e32 vcc, s92, v48
	s_nop 0
	v_cndmask_b32_e64 v49, v49, v50, s[4:5]
	v_rsq_f32_e32 v49, v49
	s_nop 0
	v_mul_f32_e32 v50, 0x45800000, v49
	v_cndmask_b32_e64 v50, v49, v50, s[4:5]
	v_mul_f32_e32 v49, 0x4b800000, v48
	v_cndmask_b32_e32 v48, v48, v49, vcc
	v_rsq_f32_e32 v48, v48
	v_pk_fma_f32 v[152:153], v[78:79], v[50:51], v[46:47] op_sel_hi:[1,0,1]
	v_pk_fma_f32 v[154:155], v[76:77], v[50:51], v[44:45] op_sel_hi:[1,0,1]
	v_pk_fma_f32 v[108:109], v[74:75], v[50:51], v[42:43] op_sel_hi:[1,0,1]
	v_mul_f32_e32 v49, 0x45800000, v48
	v_cndmask_b32_e32 v48, v48, v49, vcc
	v_pk_fma_f32 v[150:151], v[72:73], v[50:51], v[40:41] op_sel_hi:[1,0,1]
	v_pk_fma_f32 v[76:77], v[70:71], v[50:51], v[38:39] op_sel_hi:[1,0,1]
	v_pk_fma_f32 v[78:79], v[68:69], v[50:51], v[36:37] op_sel_hi:[1,0,1]
	v_pk_fma_f32 v[72:73], v[66:67], v[50:51], v[34:35] op_sel_hi:[1,0,1]
	v_pk_fma_f32 v[74:75], v[64:65], v[50:51], v[32:33] op_sel_hi:[1,0,1]
	v_pk_fma_f32 v[68:69], v[62:63], v[48:49], v[46:47] op_sel_hi:[1,0,1]
	v_pk_fma_f32 v[70:71], v[60:61], v[48:49], v[44:45] op_sel_hi:[1,0,1]
	v_pk_fma_f32 v[64:65], v[58:59], v[48:49], v[42:43] op_sel_hi:[1,0,1]
	v_pk_fma_f32 v[66:67], v[56:57], v[48:49], v[40:41] op_sel_hi:[1,0,1]
	v_pk_fma_f32 v[60:61], v[54:55], v[48:49], v[38:39] op_sel_hi:[1,0,1]
	v_pk_fma_f32 v[62:63], v[52:53], v[48:49], v[36:37] op_sel_hi:[1,0,1]
	v_pk_fma_f32 v[56:57], v[174:175], v[48:49], v[34:35] op_sel_hi:[1,0,1]
	v_pk_fma_f32 v[58:59], v[172:173], v[48:49], v[32:33] op_sel_hi:[1,0,1]
	v_max_f32_e32 v78, 0, v78
	v_max_f32_e32 v79, 0, v79
	v_max_f32_e32 v76, 0, v76
	v_max_f32_e32 v77, 0, v77
	v_max_f32_e32 v74, 0, v74
	v_max_f32_e32 v75, 0, v75
	v_max_f32_e32 v72, 0, v72
	v_max_f32_e32 v73, 0, v73
	v_pk_mul_f32 v[78:79], v[78:79], v[78:79]
	v_pk_mul_f32 v[76:77], v[76:77], v[76:77]
	v_pk_mul_f32 v[74:75], v[74:75], v[74:75]
	v_pk_mul_f32 v[72:73], v[72:73], v[72:73]
	v_cvt_pk_bf16_f32 v78, v78, v79
	v_cvt_pk_bf16_f32 v79, v76, v77
	v_cvt_pk_bf16_f32 v74, v74, v75
	v_cvt_pk_bf16_f32 v75, v72, v73
	v_max_f32_e32 v70, 0, v70
	v_max_f32_e32 v71, 0, v71
	v_max_f32_e32 v68, 0, v68
	v_max_f32_e32 v69, 0, v69
	v_max_f32_e32 v66, 0, v66
	v_max_f32_e32 v67, 0, v67
	v_max_f32_e32 v64, 0, v64
	v_max_f32_e32 v65, 0, v65
	v_max_f32_e32 v62, 0, v62
	v_max_f32_e32 v63, 0, v63
	v_max_f32_e32 v60, 0, v60
	v_max_f32_e32 v61, 0, v61
	v_max_f32_e32 v58, 0, v58
	v_max_f32_e32 v59, 0, v59
	v_max_f32_e32 v56, 0, v56
	v_max_f32_e32 v57, 0, v57
	v_pk_mul_f32 v[70:71], v[70:71], v[70:71]
	v_pk_mul_f32 v[68:69], v[68:69], v[68:69]
	v_pk_mul_f32 v[66:67], v[66:67], v[66:67]
	v_pk_mul_f32 v[64:65], v[64:65], v[64:65]
	v_pk_mul_f32 v[62:63], v[62:63], v[62:63]
	v_pk_mul_f32 v[60:61], v[60:61], v[60:61]
	v_pk_mul_f32 v[58:59], v[58:59], v[58:59]
	v_pk_mul_f32 v[56:57], v[56:57], v[56:57]
	v_cvt_pk_bf16_f32 v70, v70, v71
	v_cvt_pk_bf16_f32 v71, v68, v69
	v_cvt_pk_bf16_f32 v66, v66, v67
	v_cvt_pk_bf16_f32 v67, v64, v65
	v_cvt_pk_bf16_f32 v62, v62, v63
	v_cvt_pk_bf16_f32 v63, v60, v61
	v_cvt_pk_bf16_f32 v58, v58, v59
	v_cvt_pk_bf16_f32 v59, v56, v57
	s_waitcnt vmcnt(0)
; DI unsigned pk2(float a, float b) { f32x2 v = {a, b}; bf2_t r = __builtin_convertvector(v, bf2_t); return __builtin_bit_cast(unsigned, r); }
;     static DI void run(const f32x4 (&acc)[8][4], const TileCtx& tc, const Params& p, ldsp_t wb) {
; #pragma unroll
;         for (int h = 0; h < 2; ++h) {
; #pragma unroll
;             for (int mm = 0; mm < 4; ++mm) {
;                 const int m = h * 4 + mm;
; #pragma unroll
;                 for (int n = 0; n < 4; ++n) {
;                     f32x4 a = acc[m][n];
; #pragma unroll
;                     for (int j = 0; j < 4; ++j) { const float r = fmaxf(a[j], 0.f); a[j] = r * r; }
;                     u32x2 w; w[0] = pk2(a[0], a[1]); w[1] = pk2(a[2], a[3]);
;                     wave_put(wb, mm * 16 + tc.fr, n, tc.fq, w);
;                 }
;             }
;             wave_rows_store(wb, tc.lane, p.ACT + (size_t)(tc.brow + tc.wr * 128 + h * 64) * FF + tc.bcol + tc.wc * 64, FF);
	v_mov_b64_e32 v[48:49], v[218:219]
	v_mov_b64_e32 v[50:51], v[220:221]
	v_mov_b64_e32 v[52:53], v[222:223]
	v_mov_b64_e32 v[54:55], v[224:225]
	v_mov_b32_e32 v145, v48
	v_mov_b32_e32 v144, v52
	v_mov_b32_e32 v48, v53
	v_pk_add_f32 v[48:49], v[144:145], v[48:49]
	v_mov_b32_e32 v52, v54
	v_mov_b32_e32 v53, v50
	v_pk_add_f32 v[48:49], v[52:53], v[48:49]
	v_mov_b32_e32 v50, v55
	v_pk_add_f32 v[48:49], v[50:51], v[48:49]
	ds_bpermute_b32 v51, v162, v49
	ds_bpermute_b32 v50, v162, v48
	s_waitcnt lgkmcnt(0)
	v_pk_add_f32 v[48:49], v[48:49], v[50:51]
	ds_bpermute_b32 v51, v161, v49
	ds_bpermute_b32 v50, v161, v48
	s_waitcnt lgkmcnt(0)
	v_pk_add_f32 v[48:49], v[48:49], v[50:51]
	s_nop 0
	v_pk_fma_f32 v[48:49], v[48:49], s[16:17], v[166:167] op_sel_hi:[1,0,0]
	s_nop 0
	v_mul_f32_e32 v50, 0x4b800000, v49
	v_cmp_gt_f32_e64 s[4:5], s92, v49
	v_cmp_gt_f32_e32 vcc, s92, v48
	s_nop 0
	v_cndmask_b32_e64 v49, v49, v50, s[4:5]
	v_rsq_f32_e32 v49, v49
	s_nop 0
	v_mul_f32_e32 v50, 0x45800000, v49
	v_cndmask_b32_e64 v50, v49, v50, s[4:5]
	v_mul_f32_e32 v49, 0x4b800000, v48
	v_cndmask_b32_e32 v48, v48, v49, vcc
	v_rsq_f32_e32 v48, v48
	v_pk_fma_f32 v[18:19], v[18:19], v[50:51], v[34:35] op_sel_hi:[1,0,1]
	v_pk_fma_f32 v[16:17], v[16:17], v[50:51], v[32:33] op_sel_hi:[1,0,1]
	v_pk_fma_f32 v[20:21], v[20:21], v[50:51], v[36:37] op_sel_hi:[1,0,1]
	v_mul_f32_e32 v49, 0x45800000, v48
	v_cndmask_b32_e32 v48, v48, v49, vcc
	v_pk_fma_f32 v[2:3], v[2:3], v[48:49], v[34:35] op_sel_hi:[1,0,1]
	v_pk_fma_f32 v[0:1], v[0:1], v[48:49], v[32:33] op_sel_hi:[1,0,1]
	v_max_f32_e32 v32, 0, v164
	v_max_f32_e32 v33, 0, v165
	v_max_f32_e32 v34, 0, v142
	v_max_f32_e32 v35, 0, v143
	v_pk_fma_f32 v[4:5], v[4:5], v[48:49], v[36:37] op_sel_hi:[1,0,1]
	v_pk_mul_f32 v[32:33], v[32:33], v[32:33]
	v_pk_mul_f32 v[34:35], v[34:35], v[34:35]
	v_bfe_u32 v37, v158, 5, 1
	v_add_u32_e32 v36, 0x10000, v160
	v_cvt_pk_bf16_f32 v32, v32, v33
	v_cvt_pk_bf16_f32 v33, v34, v35
	v_bitop3_b32 v34, v37, v158, 7 bitop3:0x78
	v_lshrrev_b32_e32 v35, 1, v158
	v_pk_fma_f32 v[24:25], v[24:25], v[50:51], v[40:41] op_sel_hi:[1,0,1]
	v_pk_fma_f32 v[22:23], v[22:23], v[50:51], v[38:39] op_sel_hi:[1,0,1]
	v_pk_fma_f32 v[8:9], v[8:9], v[48:49], v[40:41] op_sel_hi:[1,0,1]
	v_pk_fma_f32 v[6:7], v[6:7], v[48:49], v[38:39] op_sel_hi:[1,0,1]
	v_lshl_or_b32 v38, v159, 7, v36
	v_lshlrev_b32_e32 v34, 4, v34
	v_and_b32_e32 v40, 8, v35
	v_or3_b32 v52, v38, v34, v40
	ds_write_b64 v52, v[32:33]
	v_max_f32_e32 v32, 0, v140
	v_max_f32_e32 v33, 0, v141
	v_max_f32_e32 v34, 0, v138
	v_max_f32_e32 v35, 0, v139
	v_and_b32_e32 v39, 7, v158
	v_pk_mul_f32 v[32:33], v[32:33], v[32:33]
	v_pk_mul_f32 v[34:35], v[34:35], v[34:35]
	v_cvt_pk_bf16_f32 v32, v32, v33
	v_cvt_pk_bf16_f32 v33, v34, v35
	v_bitop3_b32 v34, v37, v39, 2 bitop3:0x36
	v_lshlrev_b32_e32 v34, 4, v34
	v_or3_b32 v53, v38, v34, v40
	ds_write_b64 v53, v[32:33]
	v_max_f32_e32 v32, 0, v136
	v_max_f32_e32 v33, 0, v137
	v_max_f32_e32 v34, 0, v134
	v_max_f32_e32 v35, 0, v135
	v_pk_mul_f32 v[32:33], v[32:33], v[32:33]
	v_pk_mul_f32 v[34:35], v[34:35], v[34:35]
	v_cvt_pk_bf16_f32 v32, v32, v33
	v_cvt_pk_bf16_f32 v33, v34, v35
	v_bitop3_b32 v34, v37, v39, 4 bitop3:0x36
	v_lshlrev_b32_e32 v34, 4, v34
	v_or3_b32 v54, v38, v34, v40
	ds_write_b64 v54, v[32:33]
	v_max_f32_e32 v32, 0, v132
	v_max_f32_e32 v33, 0, v133
	v_max_f32_e32 v34, 0, v130
	v_max_f32_e32 v35, 0, v131
	v_pk_mul_f32 v[32:33], v[32:33], v[32:33]
	v_pk_mul_f32 v[34:35], v[34:35], v[34:35]
	v_cvt_pk_bf16_f32 v32, v32, v33
	v_cvt_pk_bf16_f32 v33, v34, v35
	v_bitop3_b32 v34, v37, v39, 6 bitop3:0x36
	v_lshlrev_b32_e32 v34, 4, v34
	v_or3_b32 v55, v38, v34, v40
	ds_write_b64 v55, v[32:33]
	v_max_f32_e32 v32, 0, v128
	v_max_f32_e32 v33, 0, v129
	v_max_f32_e32 v34, 0, v126
	v_max_f32_e32 v35, 0, v127
	v_pk_mul_f32 v[32:33], v[32:33], v[32:33]
	v_pk_mul_f32 v[34:35], v[34:35], v[34:35]
	v_cvt_pk_bf16_f32 v32, v32, v33
	v_cvt_pk_bf16_f32 v33, v34, v35
	ds_write_b64 v52, v[32:33] offset:2048
	v_max_f32_e32 v32, 0, v124
	v_max_f32_e32 v33, 0, v125
	v_max_f32_e32 v34, 0, v122
	v_max_f32_e32 v35, 0, v123
	v_pk_mul_f32 v[32:33], v[32:33], v[32:33]
	v_pk_mul_f32 v[34:35], v[34:35], v[34:35]
	v_cvt_pk_bf16_f32 v32, v32, v33
	v_cvt_pk_bf16_f32 v33, v34, v35
	ds_write_b64 v53, v[32:33] offset:2048
	v_max_f32_e32 v32, 0, v120
	v_max_f32_e32 v33, 0, v121
	v_max_f32_e32 v34, 0, v118
	v_max_f32_e32 v35, 0, v119
	v_pk_mul_f32 v[32:33], v[32:33], v[32:33]
	v_pk_mul_f32 v[34:35], v[34:35], v[34:35]
	v_cvt_pk_bf16_f32 v32, v32, v33
	v_cvt_pk_bf16_f32 v33, v34, v35
	ds_write_b64 v54, v[32:33] offset:2048
	v_max_f32_e32 v32, 0, v116
	v_max_f32_e32 v33, 0, v117
	v_max_f32_e32 v34, 0, v114
	v_max_f32_e32 v35, 0, v115
	v_pk_mul_f32 v[32:33], v[32:33], v[32:33]
	v_pk_mul_f32 v[34:35], v[34:35], v[34:35]
	v_cvt_pk_bf16_f32 v32, v32, v33
	v_cvt_pk_bf16_f32 v33, v34, v35
	ds_write_b64 v55, v[32:33] offset:2048
	v_max_f32_e32 v32, 0, v148
	v_max_f32_e32 v33, 0, v149
	v_max_f32_e32 v34, 0, v110
	v_max_f32_e32 v35, 0, v111
	v_pk_mul_f32 v[32:33], v[32:33], v[32:33]
	v_pk_mul_f32 v[34:35], v[34:35], v[34:35]
	v_cvt_pk_bf16_f32 v32, v32, v33
	v_cvt_pk_bf16_f32 v33, v34, v35
	ds_write_b64 v52, v[32:33] offset:4096
	v_max_f32_e32 v32, 0, v104
	v_max_f32_e32 v33, 0, v105
	v_max_f32_e32 v34, 0, v106
	v_max_f32_e32 v35, 0, v107
	v_pk_mul_f32 v[32:33], v[32:33], v[32:33]
	v_pk_mul_f32 v[34:35], v[34:35], v[34:35]
	v_cvt_pk_bf16_f32 v32, v32, v33
	v_cvt_pk_bf16_f32 v33, v34, v35
	ds_write_b64 v53, v[32:33] offset:4096
	v_max_f32_e32 v32, 0, v100
	v_max_f32_e32 v33, 0, v101
	v_max_f32_e32 v34, 0, v102
	v_max_f32_e32 v35, 0, v103
	v_pk_mul_f32 v[32:33], v[32:33], v[32:33]
; #define LDSP __attribute__((address_space(3)))
; DI unsigned pk2(float a, float b) { f32x2 v = {a, b}; bf2_t r = __builtin_convertvector(v, bf2_t); return __builtin_bit_cast(unsigned, r); }
; DI void wave_rows_store(ldsp_t wb, int lane, bf16_t* dst0, size_t ld) {
; #pragma unroll
;     for (int i = 0; i < 8; ++i) {
;         const int row = i * 8 + (lane >> 3), ch = lane & 7;
;         const u32x4 v = *(const LDSP u32x4*)(wb + row * 128 + ((ch ^ (row & 7)) << 4));
;         *(u32x4*)(dst0 + (size_t)row * ld + ch * 8) = v;
;     }
; }
;     static DI void run(const f32x4 (&acc)[8][4], const TileCtx& tc, const Params& p, ldsp_t wb) {
;     ...
;             for (int mm = 0; mm < 4; ++mm) {
;                 const int m = h * 4 + mm;
; #pragma unroll
;                 for (int n = 0; n < 4; ++n) {
;                     f32x4 a = acc[m][n];
; #pragma unroll
;                     for (int j = 0; j < 4; ++j) { const float r = fmaxf(a[j], 0.f); a[j] = r * r; }
;                     u32x2 w; w[0] = pk2(a[0], a[1]); w[1] = pk2(a[2], a[3]);
;                     wave_put(wb, mm * 16 + tc.fr, n, tc.fq, w);
;                 }
;             }
;             wave_rows_store(wb, tc.lane, p.ACT + (size_t)(tc.brow + tc.wr * 128 + h * 64) * FF + tc.bcol + tc.wc * 64, FF);
	v_pk_mul_f32 v[34:35], v[34:35], v[34:35]
	v_cvt_pk_bf16_f32 v32, v32, v33
	v_cvt_pk_bf16_f32 v33, v34, v35
	ds_write_b64 v54, v[32:33] offset:4096
	v_max_f32_e32 v32, 0, v96
	v_max_f32_e32 v33, 0, v97
	v_max_f32_e32 v34, 0, v98
	v_max_f32_e32 v35, 0, v99
	v_pk_mul_f32 v[32:33], v[32:33], v[32:33]
	v_pk_mul_f32 v[34:35], v[34:35], v[34:35]
	v_cvt_pk_bf16_f32 v32, v32, v33
	v_cvt_pk_bf16_f32 v33, v34, v35
	ds_write_b64 v55, v[32:33] offset:4096
	v_max_f32_e32 v32, 0, v92
	v_max_f32_e32 v33, 0, v93
	v_max_f32_e32 v34, 0, v94
	v_max_f32_e32 v35, 0, v95
	v_pk_mul_f32 v[32:33], v[32:33], v[32:33]
	v_pk_mul_f32 v[34:35], v[34:35], v[34:35]
	v_cvt_pk_bf16_f32 v32, v32, v33
	v_cvt_pk_bf16_f32 v33, v34, v35
	ds_write_b64 v52, v[32:33] offset:6144
	v_max_f32_e32 v32, 0, v88
	v_max_f32_e32 v33, 0, v89
	v_max_f32_e32 v34, 0, v90
	v_max_f32_e32 v35, 0, v91
	v_pk_mul_f32 v[32:33], v[32:33], v[32:33]
	v_pk_mul_f32 v[34:35], v[34:35], v[34:35]
	v_cvt_pk_bf16_f32 v32, v32, v33
	v_cvt_pk_bf16_f32 v33, v34, v35
	ds_write_b64 v53, v[32:33] offset:6144
	v_max_f32_e32 v32, 0, v84
	v_max_f32_e32 v33, 0, v85
	v_max_f32_e32 v34, 0, v86
	v_max_f32_e32 v35, 0, v87
	v_pk_mul_f32 v[32:33], v[32:33], v[32:33]
	v_pk_mul_f32 v[34:35], v[34:35], v[34:35]
	v_cvt_pk_bf16_f32 v32, v32, v33
	v_cvt_pk_bf16_f32 v33, v34, v35
	ds_write_b64 v54, v[32:33] offset:6144
	v_max_f32_e32 v32, 0, v80
	v_max_f32_e32 v33, 0, v81
	v_max_f32_e32 v34, 0, v82
	v_max_f32_e32 v35, 0, v83
	v_pk_fma_f32 v[28:29], v[28:29], v[50:51], v[44:45] op_sel_hi:[1,0,1]
	v_pk_fma_f32 v[12:13], v[12:13], v[48:49], v[44:45] op_sel_hi:[1,0,1]
	v_pk_mul_f32 v[32:33], v[32:33], v[32:33]
	v_pk_mul_f32 v[34:35], v[34:35], v[34:35]
	v_add_u32_e32 v44, s35, v112
	v_cvt_pk_bf16_f32 v32, v32, v33
	v_cvt_pk_bf16_f32 v33, v34, v35
	v_ashrrev_i32_e32 v45, 31, v44
	ds_write_b64 v55, v[32:33] offset:6144
	v_lshlrev_b64 v[32:33], 13, v[44:45]
	v_bfe_u32 v45, v158, 3, 3
	v_xor_b32_e32 v34, v45, v158
	v_lshl_add_u64 v[32:33], s[12:13], 0, v[32:33]
	s_lshl_b64 s[4:5], s[42:43], 1
	v_lshlrev_b32_e32 v34, 4, v34
	v_lshl_add_u64 v[32:33], v[32:33], 0, s[4:5]
	v_and_or_b32 v86, v34, s15, v36
	v_lshlrev_b32_e32 v34, 4, v158
	v_pk_fma_f32 v[30:31], v[30:31], v[50:51], v[46:47] op_sel_hi:[1,0,1]
	v_pk_fma_f32 v[26:27], v[26:27], v[50:51], v[42:43] op_sel_hi:[1,0,1]
	v_lshl_add_u64 v[32:33], v[32:33], 0, v[192:193]
	v_and_b32_e32 v50, 0x70, v34
	v_mov_b32_e32 v51, v193
	v_lshl_or_b32 v87, v45, 7, v86
	v_lshl_add_u64 v[84:85], v[32:33], 0, v[50:51]
	ds_read_b128 v[32:35], v87
	v_pk_fma_f32 v[14:15], v[14:15], v[48:49], v[46:47] op_sel_hi:[1,0,1]
	v_pk_fma_f32 v[10:11], v[10:11], v[48:49], v[42:43] op_sel_hi:[1,0,1]
	v_lshlrev_b32_e32 v48, 13, v45
	v_mov_b32_e32 v49, v193
	v_lshl_add_u64 v[36:37], v[84:85], 0, v[48:49]
	s_waitcnt lgkmcnt(0)
	global_store_dwordx4 v[36:37], v[32:35], off
	v_or_b32_e32 v36, 8, v45
	v_lshl_or_b32 v88, v36, 7, v86
	ds_read_b128 v[32:35], v88
	v_lshlrev_b32_e32 v46, 13, v36
	v_mov_b32_e32 v47, v193
	v_lshl_add_u64 v[36:37], v[84:85], 0, v[46:47]
	v_mov_b32_e32 v43, v193
	s_waitcnt lgkmcnt(0)
	global_store_dwordx4 v[36:37], v[32:35], off
	v_or_b32_e32 v36, 16, v45
	v_lshl_or_b32 v89, v36, 7, v86
	ds_read_b128 v[32:35], v89
	v_lshlrev_b32_e32 v42, 13, v36
	v_lshl_add_u64 v[36:37], v[84:85], 0, v[42:43]
	v_mov_b32_e32 v41, v193
	v_max_f32_e32 v0, 0, v0
	s_waitcnt lgkmcnt(0)
	global_store_dwordx4 v[36:37], v[32:35], off
	v_or_b32_e32 v36, 24, v45
	v_lshl_or_b32 v90, v36, 7, v86
	ds_read_b128 v[32:35], v90
	v_lshlrev_b32_e32 v40, 13, v36
	v_lshl_add_u64 v[36:37], v[84:85], 0, v[40:41]
	v_max_f32_e32 v1, 0, v1
	v_max_f32_e32 v2, 0, v2
	s_waitcnt lgkmcnt(0)
	global_store_dwordx4 v[36:37], v[32:35], off
	v_max_f32_e32 v3, 0, v3
	v_pk_mul_f32 v[0:1], v[0:1], v[0:1]
	v_or_b32_e32 v32, 32, v45
	v_lshl_or_b32 v91, v32, 7, v86
	ds_read_b128 v[36:39], v91
	v_lshlrev_b32_e32 v34, 13, v32
	v_mov_b32_e32 v35, v193
	v_lshl_add_u64 v[32:33], v[84:85], 0, v[34:35]
	v_pk_mul_f32 v[2:3], v[2:3], v[2:3]
	s_waitcnt lgkmcnt(0)
	global_store_dwordx4 v[32:33], v[36:39], off
	v_or_b32_e32 v32, 40, v45
	v_lshl_or_b32 v92, v32, 7, v86
	ds_read_b128 v[80:83], v92
	v_lshlrev_b32_e32 v38, 13, v32
	v_mov_b32_e32 v39, v193
	v_lshl_add_u64 v[32:33], v[84:85], 0, v[38:39]
	v_mov_b32_e32 v37, v193
	s_waitcnt lgkmcnt(0)
	global_store_dwordx4 v[32:33], v[80:83], off
	v_or_b32_e32 v32, 48, v45
	v_lshl_or_b32 v93, v32, 7, v86
	ds_read_b128 v[80:83], v93
	v_lshlrev_b32_e32 v36, 13, v32
	v_lshl_add_u64 v[32:33], v[84:85], 0, v[36:37]
	v_cvt_pk_bf16_f32 v0, v0, v1
	v_cvt_pk_bf16_f32 v1, v2, v3
	s_waitcnt lgkmcnt(0)
; #define LDSP __attribute__((address_space(3)))
; DI unsigned pk2(float a, float b) { f32x2 v = {a, b}; bf2_t r = __builtin_convertvector(v, bf2_t); return __builtin_bit_cast(unsigned, r); }
; DI void wave_rows_store(ldsp_t wb, int lane, bf16_t* dst0, size_t ld) {
; #pragma unroll
;     for (int i = 0; i < 8; ++i) {
;         const int row = i * 8 + (lane >> 3), ch = lane & 7;
;         const u32x4 v = *(const LDSP u32x4*)(wb + row * 128 + ((ch ^ (row & 7)) << 4));
;         *(u32x4*)(dst0 + (size_t)row * ld + ch * 8) = v;
;     }
; }
;     static DI void run(const f32x4 (&acc)[8][4], const TileCtx& tc, const Params& p, ldsp_t wb) {
;     ...
;             for (int mm = 0; mm < 4; ++mm) {
;                 const int m = h * 4 + mm;
; #pragma unroll
;                 for (int n = 0; n < 4; ++n) {
;                     f32x4 a = acc[m][n];
; #pragma unroll
;                     for (int j = 0; j < 4; ++j) { const float r = fmaxf(a[j], 0.f); a[j] = r * r; }
;                     u32x2 w; w[0] = pk2(a[0], a[1]); w[1] = pk2(a[2], a[3]);
;                     wave_put(wb, mm * 16 + tc.fr, n, tc.fq, w);
;                 }
;             }
;             wave_rows_store(wb, tc.lane, p.ACT + (size_t)(tc.brow + tc.wr * 128 + h * 64) * FF + tc.bcol + tc.wc * 64, FF);
	global_store_dwordx4 v[32:33], v[80:83], off
	v_or_b32_e32 v32, 56, v45
	v_lshl_or_b32 v45, v32, 7, v86
	ds_read_b128 v[80:83], v45
	v_lshlrev_b32_e32 v32, 13, v32
	v_mov_b32_e32 v33, v193
	v_lshl_add_u64 v[84:85], v[84:85], 0, v[32:33]
	ds_write_b64 v55, v[0:1] offset:6144
	s_waitcnt lgkmcnt(1)
	global_store_dwordx4 v[84:85], v[80:83], off
	v_or_b32_e32 v0, 64, v44
	v_ashrrev_i32_e32 v1, 31, v0
	v_max_f32_e32 v80, 0, v154
	v_max_f32_e32 v81, 0, v155
	v_max_f32_e32 v82, 0, v152
	v_max_f32_e32 v83, 0, v153
	v_pk_mul_f32 v[80:81], v[80:81], v[80:81]
	v_pk_mul_f32 v[82:83], v[82:83], v[82:83]
	v_cvt_pk_bf16_f32 v80, v80, v81
	v_cvt_pk_bf16_f32 v81, v82, v83
	ds_write_b64 v52, v[80:81]
	v_max_f32_e32 v80, 0, v150
	v_max_f32_e32 v81, 0, v151
	v_max_f32_e32 v82, 0, v108
	v_max_f32_e32 v83, 0, v109
	v_lshlrev_b64 v[0:1], 13, v[0:1]
	v_pk_mul_f32 v[80:81], v[80:81], v[80:81]
	v_pk_mul_f32 v[82:83], v[82:83], v[82:83]
	v_max_f32_e32 v4, 0, v4
	v_max_f32_e32 v5, 0, v5
	v_max_f32_e32 v6, 0, v6
	v_max_f32_e32 v7, 0, v7
	v_lshl_add_u64 v[0:1], s[12:13], 0, v[0:1]
	v_cvt_pk_bf16_f32 v80, v80, v81
	v_cvt_pk_bf16_f32 v81, v82, v83
	v_pk_mul_f32 v[4:5], v[4:5], v[4:5]
	v_pk_mul_f32 v[6:7], v[6:7], v[6:7]
	v_lshl_add_u64 v[0:1], v[0:1], 0, s[4:5]
	ds_write_b64 v53, v[80:81]
	ds_write_b64 v54, v[78:79]
	ds_write_b64 v55, v[74:75]
	v_cvt_pk_bf16_f32 v4, v4, v5
	v_cvt_pk_bf16_f32 v5, v6, v7
	v_lshl_add_u64 v[0:1], v[0:1], 0, v[192:193]
	ds_write_b64 v54, v[4:5] offset:6144
	v_lshl_add_u64 v[4:5], v[0:1], 0, v[50:51]
	ds_read_b128 v[0:3], v87
	v_lshl_add_u64 v[6:7], v[4:5], 0, v[48:49]
	ds_write_b64 v52, v[70:71] offset:2048
	ds_write_b64 v53, v[66:67] offset:2048
	ds_write_b64 v54, v[62:63] offset:2048
	s_waitcnt lgkmcnt(3)
	global_store_dwordx4 v[6:7], v[0:3], off
	ds_read_b128 v[0:3], v88
	ds_write_b64 v55, v[58:59] offset:2048
	v_lshl_add_u64 v[6:7], v[4:5], 0, v[46:47]
	v_max_f32_e32 v28, 0, v28
	v_max_f32_e32 v29, 0, v29
	s_waitcnt lgkmcnt(1)
	global_store_dwordx4 v[6:7], v[0:3], off
	ds_read_b128 v[0:3], v89
	v_lshl_add_u64 v[6:7], v[4:5], 0, v[42:43]
	v_max_f32_e32 v30, 0, v30
	v_max_f32_e32 v31, 0, v31
	v_max_f32_e32 v24, 0, v24
	s_waitcnt lgkmcnt(0)
	global_store_dwordx4 v[6:7], v[0:3], off
	ds_read_b128 v[0:3], v90
	v_max_f32_e32 v25, 0, v25
	v_max_f32_e32 v26, 0, v26
	v_max_f32_e32 v27, 0, v27
	v_max_f32_e32 v20, 0, v20
	v_max_f32_e32 v21, 0, v21
	v_max_f32_e32 v22, 0, v22
	v_max_f32_e32 v23, 0, v23
	v_max_f32_e32 v16, 0, v16
	v_max_f32_e32 v17, 0, v17
	v_max_f32_e32 v18, 0, v18
	v_max_f32_e32 v19, 0, v19
	v_pk_mul_f32 v[28:29], v[28:29], v[28:29]
	v_pk_mul_f32 v[30:31], v[30:31], v[30:31]
	v_pk_mul_f32 v[24:25], v[24:25], v[24:25]
	v_pk_mul_f32 v[26:27], v[26:27], v[26:27]
	v_pk_mul_f32 v[20:21], v[20:21], v[20:21]
	v_pk_mul_f32 v[22:23], v[22:23], v[22:23]
	v_pk_mul_f32 v[16:17], v[16:17], v[16:17]
	v_pk_mul_f32 v[18:19], v[18:19], v[18:19]
	v_cvt_pk_bf16_f32 v28, v28, v29
	v_cvt_pk_bf16_f32 v29, v30, v31
	v_cvt_pk_bf16_f32 v24, v24, v25
	v_cvt_pk_bf16_f32 v25, v26, v27
	v_cvt_pk_bf16_f32 v20, v20, v21
	v_cvt_pk_bf16_f32 v21, v22, v23
	v_cvt_pk_bf16_f32 v16, v16, v17
	v_cvt_pk_bf16_f32 v17, v18, v19
	ds_write_b64 v52, v[28:29] offset:4096
	ds_write_b64 v53, v[24:25] offset:4096
	ds_write_b64 v54, v[20:21] offset:4096
	ds_write_b64 v55, v[16:17] offset:4096
	v_lshl_add_u64 v[6:7], v[4:5], 0, v[40:41]
	s_waitcnt lgkmcnt(4)
	global_store_dwordx4 v[6:7], v[0:3], off
	ds_read_b128 v[0:3], v91
	v_lshl_add_u64 v[6:7], v[4:5], 0, v[34:35]
	v_max_f32_e32 v12, 0, v12
	v_max_f32_e32 v13, 0, v13
	v_max_f32_e32 v14, 0, v14
	s_waitcnt lgkmcnt(0)
	global_store_dwordx4 v[6:7], v[0:3], off
	ds_read_b128 v[0:3], v92
	v_max_f32_e32 v15, 0, v15
	v_max_f32_e32 v8, 0, v8
	v_max_f32_e32 v9, 0, v9
	v_max_f32_e32 v10, 0, v10
	v_max_f32_e32 v11, 0, v11
	v_pk_mul_f32 v[12:13], v[12:13], v[12:13]
	v_pk_mul_f32 v[14:15], v[14:15], v[14:15]
	v_pk_mul_f32 v[8:9], v[8:9], v[8:9]
	v_pk_mul_f32 v[10:11], v[10:11], v[10:11]
	v_cvt_pk_bf16_f32 v12, v12, v13
	v_cvt_pk_bf16_f32 v13, v14, v15
	v_cvt_pk_bf16_f32 v8, v8, v9
	v_cvt_pk_bf16_f32 v9, v10, v11
	ds_write_b64 v52, v[12:13] offset:6144
	ds_write_b64 v53, v[8:9] offset:6144
	v_lshl_add_u64 v[6:7], v[4:5], 0, v[38:39]
	s_waitcnt lgkmcnt(2)
	global_store_dwordx4 v[6:7], v[0:3], off
	ds_read_b128 v[0:3], v93
	v_lshl_add_u64 v[6:7], v[4:5], 0, v[36:37]
	v_lshl_add_u64 v[4:5], v[4:5], 0, v[32:33]
	s_and_b64 vcc, exec, s[6:7]
	s_waitcnt lgkmcnt(0)
	global_store_dwordx4 v[6:7], v[0:3], off
	ds_read_b128 v[0:3], v45
	s_waitcnt lgkmcnt(0)
	global_store_dwordx4 v[4:5], v[0:3], off
	s_barrier
	s_cbranch_vccnz .LBB0_117
